# v81 = v80 + sb early-exit test: cndmask/cmp_ne re-derivation of the lane mask replaced by one s_mov (7.12 ballot trim, 3 sites, exact)
# baseline (speedup 1.0000x reference)
.LBB0_226:
	s_or_b64 exec, exec, s[12:13]
	s_lshl_b32 s0, s5, 8
	s_and_b32 s0, s0, 0xf00
	ds_read_b128 v[64:67], v221
	ds_read_b128 v[68:71], v221 offset:64
	ds_read_b128 v[76:79], v221 offset:2304
	ds_read_b128 v[80:83], v221 offset:2368
	v_or_b32_e32 v101, v168, v122
	v_or_b32_e32 v116, 3, v101
	v_cmp_lt_u32_e64 s[28:29], v116, v100
	v_or_b32_e32 v102, 16, v100
	v_cmp_lt_u32_e64 s[12:13], v101, v102
	v_cmp_lt_u32_e64 s[14:15], v116, v102
	s_waitcnt lgkmcnt(3)
	v_mfma_f32_16x16x32_bf16 v[72:75], v[64:67], v[48:51], 0
	s_waitcnt lgkmcnt(1)
	v_mfma_f32_16x16x32_bf16 v[84:87], v[76:79], v[48:51], 0
	v_mfma_f32_16x16x32_bf16 v[88:91], v[76:79], v[52:55], 0
	v_mfma_f32_16x16x32_bf16 v[72:75], v[68:71], v[56:59], v[72:75]
	v_mfma_f32_16x16x32_bf16 v[64:67], v[64:67], v[52:55], 0
	s_waitcnt lgkmcnt(0)
	v_mfma_f32_16x16x32_bf16 v[76:79], v[80:83], v[56:59], v[84:87]
	s_nop 4
	v_mul_f32_e64 v92, |v75|, s51
	v_mfma_f32_16x16x32_bf16 v[80:83], v[80:83], v[60:63], v[88:91]
	v_max_f32_e32 v113, 0, v73
	v_max_f32_e32 v84, v72, v72
	s_nop 0
	v_mul_f32_e64 v88, |v73|, s51
	v_mfma_f32_16x16x32_bf16 v[68:71], v[68:71], v[60:63], v[64:67]
	v_exp_f32_e32 v87, v88
	v_max_f32_e32 v104, v76, v76
	v_mul_f32_e64 v110, |v79|, s51
	v_max_f32_e32 v89, v74, v74
	v_add_f32_e32 v87, 1.0, v87
	s_nop 2
	v_max_f32_e32 v97, v70, v70
	v_mul_f32_e64 v90, |v74|, s51
	v_max_f32_e32 v91, v75, v75
	v_max_f32_e32 v93, v68, v68
	v_mul_f32_e64 v94, |v68|, s51
	v_mul_f32_e64 v96, |v69|, s51
	v_mul_f32_e64 v98, |v70|, s51
	v_mul_f32_e64 v107, |v77|, s51
	v_max_f32_e32 v111, 0, v84
	v_max_f32_e32 v84, 0, v97
	v_max_f32_e32 v97, 0, v104
	v_exp_f32_e32 v104, v110
	v_log_f32_e32 v87, v87
	v_mul_f32_e64 v105, |v76|, s51
	v_max_f32_e32 v114, 0, v89
	v_exp_f32_e32 v89, v90
	v_max_f32_e32 v115, 0, v91
	v_exp_f32_e32 v90, v92
	v_max_f32_e32 v92, 0, v93
	v_exp_f32_e32 v91, v94
	v_exp_f32_e32 v93, v96
	v_exp_f32_e32 v94, v98
	v_exp_f32_e32 v98, v107
	v_exp_f32_e32 v96, v105
	v_fmac_f32_e32 v113, 0x3f317218, v87
	v_add_f32_e32 v87, 1.0, v104
	v_mul_f32_e64 v103, |v71|, s51
	v_add_f32_e32 v93, 1.0, v93
	v_add_f32_e32 v107, 1.0, v98
	v_log_f32_e32 v87, v87
	v_or_b32_e32 v85, 16, v101
	v_max_f32_e32 v88, 0, v69
	v_exp_f32_e32 v95, v103
	v_max_f32_e32 v103, 0, v77
	v_add_f32_e32 v106, 1.0, v96
	v_log_f32_e32 v96, v93
	v_log_f32_e32 v93, v107
	v_cmp_lt_u32_e32 vcc, v85, v100
	v_mul_f32_e64 v86, |v72|, s51
	v_mul_f32_e64 v109, |v78|, s51
	v_max_f32_e32 v104, 0, v79
	v_mul_f32_e64 v85, |v80|, s51
	v_exp_f32_e32 v112, v86
	v_max_f32_e32 v86, 0, v71
	v_exp_f32_e32 v99, v109
	v_exp_f32_e32 v85, v85
	v_fmac_f32_e32 v104, 0x3f317218, v87
	v_add_f32_e32 v89, 1.0, v89
	v_fmac_f32_e32 v103, 0x3f317218, v93
	v_max_f32_e32 v93, 0, v80
	v_mul_f32_e64 v87, |v81|, s51
	v_add_f32_e32 v91, 1.0, v91
	v_log_f32_e32 v89, v89
	v_exp_f32_e32 v87, v87
	v_log_f32_e32 v98, v91
	v_log_f32_e32 v91, v106
	v_add_f32_e32 v90, 1.0, v90
	v_add_f32_e32 v94, 1.0, v94
	v_add_f32_e32 v95, 1.0, v95
	v_add_f32_e32 v99, 1.0, v99
	v_add_f32_e32 v85, 1.0, v85
	v_log_f32_e32 v109, v90
	v_log_f32_e32 v90, v94
	v_log_f32_e32 v94, v95
	v_log_f32_e32 v95, v99
	v_log_f32_e32 v99, v85
	v_fmac_f32_e32 v114, 0x3f317218, v89
	v_max_f32_e32 v89, 0, v81
	v_add_f32_e32 v85, 1.0, v87
	v_mul_f32_e64 v87, |v82|, s51
	v_fmac_f32_e32 v97, 0x3f317218, v91
	v_exp_f32_e32 v91, v87
	v_cndmask_b32_e64 v106, 0, -v97, vcc
	v_log_f32_e32 v97, v85
	v_add_f32_e32 v105, 1.0, v112
	v_max_f32_e32 v87, 0, v82
	v_add_f32_e32 v85, 1.0, v91
	v_mul_f32_e64 v91, |v83|, s51
	v_log_f32_e32 v105, v105
	v_exp_f32_e32 v91, v91
	v_fmac_f32_e32 v115, 0x3f317218, v109
	v_or_b32_e32 v109, 1, v101
	v_or_b32_e32 v112, 2, v101
	v_fmac_f32_e32 v111, 0x3f317218, v105
	v_max_f32_e32 v107, 0, v78
	v_add_f32_e32 v91, 1.0, v91
	v_cmp_lt_u32_e64 s[36:37], v109, v100
	v_cmp_lt_u32_e64 s[26:27], v112, v100
	v_cndmask_b32_e64 v105, 0, -v111, s[10:11]
	v_fmac_f32_e32 v107, 0x3f317218, v95
	v_log_f32_e32 v95, v85
	v_log_f32_e32 v91, v91
	v_cndmask_b32_e64 v110, 0, -v113, s[36:37]
	v_or_b32_e32 v111, 19, v101
	v_cndmask_b32_e64 v113, 0, -v114, s[26:27]
	v_or_b32_e32 v114, 18, v101
	v_or_b32_e32 v108, 17, v101
	v_cmp_lt_u32_e64 s[30:31], v114, v100
	v_cmp_lt_u32_e64 s[34:35], v111, v100
	v_cndmask_b32_e64 v115, 0, -v115, s[28:29]
	v_cmp_lt_u32_e64 s[38:39], v108, v100
	v_cndmask_b32_e64 v107, 0, -v107, s[30:31]
	v_cndmask_b32_e64 v100, 0, -v104, s[34:35]
	v_max_f32_e32 v85, 0, v83
	v_cndmask_b32_e64 v103, 0, -v103, s[38:39]
	v_pk_fma_f32 v[92:93], v[98:99], s[62:63], v[92:93] op_sel_hi:[1,0,1]
	v_cmp_lt_u32_e64 s[18:19], v108, v102
	v_cmp_lt_u32_e64 s[20:21], v109, v102
	v_cmp_lt_u32_e64 s[16:17], v114, v102
	v_cmp_lt_u32_e64 s[22:23], v111, v102
	v_cmp_lt_u32_e64 s[24:25], v112, v102
	v_add_f32_e32 v98, v115, v113
	v_add_f32_e32 v102, v100, v107
	v_pk_fma_f32 v[86:87], v[94:95], s[62:63], v[86:87] op_sel_hi:[1,0,1]
	v_pk_fma_f32 v[84:85], v[90:91], s[62:63], v[84:85] op_sel_hi:[1,0,1]
	v_add_f32_e32 v99, v110, v98
	v_add_f32_e32 v103, v103, v102
	v_pk_fma_f32 v[88:89], v[96:97], s[62:63], v[88:89] op_sel_hi:[1,0,1]
	v_cndmask_b32_e64 v87, 0, -v87, s[16:17]
	v_cndmask_b32_e64 v86, 0, -v86, s[14:15]
	v_cndmask_b32_e64 v85, 0, -v85, s[22:23]
	v_cndmask_b32_e64 v84, 0, -v84, s[24:25]
	v_add_f32_e32 v101, v105, v99
	v_add_f32_e32 v105, v106, v103
	v_cndmask_b32_e64 v89, 0, -v89, s[18:19]
	v_cndmask_b32_e64 v88, 0, -v88, s[20:21]
	v_pk_add_f32 v[90:91], v[84:85], v[86:87]
	v_mov_b32_e32 v84, v101
	v_mov_b32_e32 v87, v101
	v_mov_b32_e32 v94, v105
	v_mov_b32_e32 v95, v105
	v_cndmask_b32_e64 v93, 0, -v93, s[10:11]
	v_cndmask_b32_e64 v92, 0, -v92, s[12:13]
	v_pk_add_f32 v[88:89], v[88:89], v[90:91]
	v_permlane16_swap_b32_e32 v84, v87
	v_permlane16_swap_b32_e32 v94, v95
	v_pk_add_f32 v[92:93], v[92:93], v[88:89]
	v_cndmask_b32_e64 v84, v84, v87, s[8:9]
	v_cndmask_b32_e64 v94, v94, v95, s[8:9]
	v_add_f32_e32 v108, v101, v84
	v_mov_b32_e32 v84, v92
	v_mov_b32_e32 v87, v92
	v_add_f32_e32 v106, v105, v94
	v_mov_b32_e32 v94, v93
	v_mov_b32_e32 v95, v93
	v_permlane16_swap_b32_e32 v84, v87
	s_nop 0
	v_permlane16_swap_b32_e32 v94, v95
	v_cndmask_b32_e64 v95, v94, v95, s[8:9]
	v_cndmask_b32_e64 v94, v84, v87, s[8:9]
	v_mov_b32_e32 v84, v108
	v_mov_b32_e32 v87, v108
	v_mov_b32_e32 v96, v106
	v_mov_b32_e32 v97, v106
	v_pk_add_f32 v[94:95], v[92:93], v[94:95]
	v_permlane32_swap_b32_e32 v84, v87
	v_permlane32_swap_b32_e32 v96, v97
	v_cndmask_b32_e64 v109, v84, v87, s[6:7]
	v_mov_b32_e32 v84, v94
	v_mov_b32_e32 v87, v94
	v_cndmask_b32_e64 v107, v96, v97, s[6:7]
	v_mov_b32_e32 v96, v95
	v_mov_b32_e32 v97, v95
	v_permlane32_swap_b32_e32 v84, v87
	s_nop 0
	v_permlane32_swap_b32_e32 v96, v97
	v_add_f32_e32 v104, v106, v107
	v_cndmask_b32_e64 v97, v96, v97, s[6:7]
	v_cndmask_b32_e64 v96, v84, v87, s[6:7]
	v_sub_f32_e32 v84, v106, v105
	v_add_f32_e32 v87, 0, v104
	v_sub_f32_e32 v106, v108, v101
	v_fmac_f32_e32 v87, v208, v106
	v_fmac_f32_e32 v87, v209, v109
	v_add_f32_e32 v72, v72, v87
	v_add_f32_e32 v73, v73, v87
	v_add_f32_e32 v72, v101, v72
	v_add_f32_e32 v73, v99, v73
	v_mul_f32_e32 v72, 0x3fb8aa3b, v72
	v_mul_f32_e32 v73, 0x3fb8aa3b, v73
	v_exp_f32_e32 v72, v72
	v_exp_f32_e32 v73, v73
	v_fma_f32 v84, v208, v84, 0
	v_fmac_f32_e32 v84, v209, v107
	v_cndmask_b32_e64 v99, 0, v72, s[10:11]
	v_cndmask_b32_e64 v101, 0, v73, s[36:37]
	v_add_f32_e32 v72, v78, v84
	v_add_f32_e32 v73, v74, v87
	v_add_f32_e32 v72, v102, v72
	v_add_f32_e32 v73, v98, v73
	v_mul_f32_e32 v72, 0x3fb8aa3b, v72
	v_mul_f32_e32 v73, 0x3fb8aa3b, v73
	v_exp_f32_e32 v72, v72
	v_exp_f32_e32 v73, v73
	v_add_f32_e32 v74, v79, v84
	v_pk_add_f32 v[106:107], v[94:95], v[96:97]
	v_cndmask_b32_e64 v78, 0, v72, s[30:31]
	v_cndmask_b32_e64 v79, 0, v73, s[26:27]
	v_pk_add_f32 v[72:73], v[94:95], v[92:93] neg_lo:[0,1] neg_hi:[0,1]
	v_add_f32_e32 v76, v76, v84
	v_fma_f32 v73, v208, v73, 0
	v_add_f32_e32 v77, v77, v84
	v_fmac_f32_e32 v73, v209, v97
	v_add_f32_e32 v84, 0, v107
	v_fmac_f32_e32 v84, v208, v72
	v_add_f32_e32 v72, v80, v73
	v_add_f32_e32 v80, v81, v73
	v_add_f32_e32 v80, v89, v80
	v_mul_f32_e32 v80, 0x3fb8aa3b, v80
	v_exp_f32_e32 v80, v80
	v_fmac_f32_e32 v84, v209, v96
	ds_read2_b64 v[64:67], v222 offset0:32 offset1:36
	v_add_f32_e32 v75, v75, v87
	v_add_f32_e32 v68, v68, v84
	v_add_f32_e32 v69, v69, v84
	v_cndmask_b32_e64 v87, 0, v80, s[18:19]
	v_add_f32_e32 v80, v82, v73
	v_add_f32_e32 v70, v70, v84
	v_add_f32_e32 v73, v83, v73
	v_add_f32_e32 v71, v71, v84
	v_add_f32_e32 v76, v105, v76
	v_add_f32_e32 v77, v103, v77
	v_add_f32_e32 v74, v100, v74
	v_add_f32_e32 v75, v115, v75
	v_add_f32_e32 v72, v93, v72
	v_add_f32_e32 v68, v92, v68
	v_add_f32_e32 v69, v88, v69
	v_add_f32_e32 v80, v91, v80
	v_add_f32_e32 v70, v90, v70
	v_add_f32_e32 v73, v85, v73
	v_add_f32_e32 v71, v86, v71
	v_mul_f32_e32 v76, 0x3fb8aa3b, v76
	v_mul_f32_e32 v77, 0x3fb8aa3b, v77
	v_mul_f32_e32 v74, 0x3fb8aa3b, v74
	v_mul_f32_e32 v75, 0x3fb8aa3b, v75
	v_mul_f32_e32 v72, 0x3fb8aa3b, v72
	v_mul_f32_e32 v68, 0x3fb8aa3b, v68
	v_mul_f32_e32 v69, 0x3fb8aa3b, v69
	v_mul_f32_e32 v80, 0x3fb8aa3b, v80
	v_mul_f32_e32 v70, 0x3fb8aa3b, v70
	v_mul_f32_e32 v73, 0x3fb8aa3b, v73
	v_mul_f32_e32 v71, 0x3fb8aa3b, v71
	v_exp_f32_e32 v76, v76
	v_exp_f32_e32 v77, v77
	v_exp_f32_e32 v74, v74
	v_exp_f32_e32 v75, v75
	v_exp_f32_e32 v72, v72
	v_exp_f32_e32 v68, v68
	v_exp_f32_e32 v69, v69
	v_exp_f32_e32 v80, v80
	v_exp_f32_e32 v70, v70
	v_exp_f32_e32 v73, v73
	v_exp_f32_e32 v71, v71
	v_cndmask_b32_e32 v76, 0, v76, vcc
	v_cndmask_b32_e64 v77, 0, v77, s[38:39]
	v_cndmask_b32_e64 v74, 0, v74, s[34:35]
	v_cndmask_b32_e64 v75, 0, v75, s[28:29]
	v_cndmask_b32_e64 v72, 0, v72, s[10:11]
	v_cndmask_b32_e64 v68, 0, v68, s[12:13]
	v_cndmask_b32_e64 v69, 0, v69, s[20:21]
	v_cndmask_b32_e64 v84, 0, v80, s[16:17]
	v_cndmask_b32_e64 v70, 0, v70, s[24:25]
	v_cndmask_b32_e64 v73, 0, v73, s[22:23]
	v_cndmask_b32_e64 v71, 0, v71, s[14:15]
	v_cvt_pk_bf16_f32 v80, v99, v101
	v_cvt_pk_bf16_f32 v81, v79, v75
	v_cvt_pk_bf16_f32 v82, v76, v77
	v_cvt_pk_bf16_f32 v83, v78, v74
	v_cvt_pk_bf16_f32 v96, v68, v69
	v_cvt_pk_bf16_f32 v97, v70, v71
	v_cvt_pk_bf16_f32 v98, v72, v87
	v_cvt_pk_bf16_f32 v99, v84, v73
	s_waitcnt lgkmcnt(0)
	v_mfma_f32_16x16x32_bf16 v[92:95], v[64:67], v[80:83], 0
	ds_read2_b64 v[100:103], v212 offset1:4
	s_add_i32 s14, s0, 0xffffff80
	s_cmp_eq_u32 s0, 0
	v_mfma_f32_16x16x32_bf16 v[76:79], v[64:67], v[96:99], 0
	ds_read2_b64 v[64:67], v210 offset1:4
	s_cselect_b64 s[12:13], -1, 0
	v_mov_b32_e32 v105, v107
	s_waitcnt lgkmcnt(0)
	v_mfma_f32_16x16x32_bf16 v[88:91], v[64:67], v[80:83], 0
	s_and_b64 s[0:1], s[12:13], exec
	s_cselect_b32 s22, 0, s14
	v_mfma_f32_16x16x32_bf16 v[72:75], v[64:67], v[96:99], 0
	ds_read2_b64 v[64:67], v211 offset1:4
	s_waitcnt lgkmcnt(0)
	v_mfma_f32_16x16x32_bf16 v[84:87], v[64:67], v[80:83], 0
	v_mfma_f32_16x16x32_bf16 v[68:71], v[64:67], v[96:99], 0
	v_add_f32_e32 v64, v108, v109
	v_mov_b32_e32 v65, v106
	v_pk_add_f32 v[104:105], v[64:65], v[104:105]
	v_mfma_f32_16x16x32_bf16 v[80:83], v[100:103], v[80:83], 0
	v_cmp_gt_f32_e32 vcc, s63, v104
	v_cmp_gt_f32_e64 s[0:1], s63, v105
	s_and_b64 s[0:1], vcc, s[0:1]
	v_mfma_f32_16x16x32_bf16 v[64:67], v[100:103], v[96:99], 0
	s_mov_b64 vcc, s[0:1]
	v_pk_add_f32 v[170:171], v[104:105], 0 op_sel_hi:[1,0]
	s_cmp_eq_u64 vcc, exec
	s_mov_b64 s[0:1], -1
	s_cbranch_scc1 .LBB0_232
	v_cmp_lt_i32_e32 vcc, s22, v168
	s_mov_b64 s[0:1], 0
	s_and_saveexec_b64 s[14:15], vcc
	s_cbranch_execz .LBB0_231
	s_and_b32 s0, s33, 0xf00
	v_add_u32_e32 v112, s0, v213
	s_mov_b64 s[16:17], 0
	v_mov_b32_e32 v113, v214
	v_mov_b32_e32 v114, v125
.LBB0_229:
	v_add_u32_e32 v96, 0, v113
	ds_read_b128 v[116:119], v96
	ds_read_b128 v[172:175], v96 offset:64
	ds_read_b128 v[224:227], v96 offset:2304
	ds_read_b128 v[228:231], v96 offset:2368
	v_add_u32_e32 v110, 0, v114
	s_waitcnt lgkmcnt(3)
	v_mfma_f32_16x16x32_bf16 v[232:235], v[116:119], v[48:51], 0
	v_add_u32_e32 v96, 0xd800, v110
	ds_read2_b64 v[100:103], v96 offset0:24 offset1:28
	v_add_u32_e32 v96, 0x109c0, v110
	s_waitcnt lgkmcnt(3)
	v_mfma_f32_16x16x32_bf16 v[232:235], v[172:175], v[56:59], v[232:235]
	v_add_u32_e32 v98, 0x109e0, v110
	ds_read_b64 v[96:97], v96
	ds_read_b64 v[98:99], v98
	v_mfma_f32_16x16x32_bf16 v[116:119], v[116:119], v[52:55], 0
	v_add_u32_e32 v104, 0x13ac0, v110
	s_nop 2
	v_mul_f32_e64 v132, |v232|, s51
	v_exp_f32_e32 v132, v132
	v_mul_f32_e64 v141, |v233|, s51
	v_exp_f32_e32 v141, v141
	v_mul_f32_e64 v143, |v234|, s51
	v_add_f32_e32 v132, 1.0, v132
	v_exp_f32_e32 v143, v143
	v_log_f32_e32 v132, v132
	v_mul_f32_e64 v149, |v235|, s51
	v_add_f32_e32 v141, 1.0, v141
	v_exp_f32_e32 v149, v149
	v_log_f32_e32 v141, v141
	v_max_f32_e32 v115, 0, v232
	v_add_f32_e32 v143, 1.0, v143
	v_fmac_f32_e32 v115, 0x3f317218, v132
	v_log_f32_e32 v143, v143
	v_max_f32_e32 v132, 0, v233
	v_add_f32_e32 v149, 1.0, v149
	v_mfma_f32_16x16x32_bf16 v[116:119], v[172:175], v[60:63], v[116:119]
	v_fmac_f32_e32 v132, 0x3f317218, v141
	v_log_f32_e32 v149, v149
	v_max_f32_e32 v141, 0, v234
	v_fmac_f32_e32 v141, 0x3f317218, v143
	v_max_f32_e32 v143, 0, v235
	v_fmac_f32_e32 v143, 0x3f317218, v149
	s_nop 1
	v_max_f32_e32 v176, 0, v116
	v_mul_f32_e64 v149, |v116|, s51
	v_exp_f32_e32 v149, v149
	s_waitcnt lgkmcnt(4)
	v_mfma_f32_16x16x32_bf16 v[236:239], v[224:227], v[48:51], 0
	v_sub_f32_e64 v141, -v141, v143
	v_sub_f32_e32 v132, v141, v132
	v_add_f32_e32 v149, 1.0, v149
	v_mfma_f32_16x16x32_bf16 v[224:227], v[224:227], v[52:55], 0
	v_sub_f32_e32 v115, v132, v115
	v_mov_b32_e32 v159, v115
	v_add_u32_e32 v106, 0x13ae0, v110
	s_waitcnt lgkmcnt(3)
	v_mfma_f32_16x16x32_bf16 v[172:175], v[228:231], v[56:59], v[236:239]
	v_add_u32_e32 v108, 0x16bc0, v110
	v_add_u32_e32 v110, 0x16be0, v110
	ds_read_b64 v[104:105], v104
	ds_read_b64 v[106:107], v106
	v_mfma_f32_16x16x32_bf16 v[224:227], v[228:231], v[60:63], v[224:227]
	v_log_f32_e32 v228, v149
	v_max_f32_e32 v230, 0, v117
	v_mul_f32_e64 v149, |v117|, s51
	v_exp_f32_e32 v149, v149
	v_mul_f32_e64 v151, |v172|, s51
	v_exp_f32_e32 v151, v151
	v_mul_f32_e64 v153, |v173|, s51
	v_add_f32_e32 v149, 1.0, v149
	v_log_f32_e32 v236, v149
	v_max_f32_e32 v238, 0, v118
	v_mul_f32_e64 v149, |v118|, s51
	v_exp_f32_e32 v149, v149
	v_exp_f32_e32 v153, v153
	v_mul_f32_e64 v155, |v174|, s51
	v_add_f32_e32 v151, 1.0, v151
	v_add_f32_e32 v149, 1.0, v149
	v_log_f32_e32 v240, v149
	v_max_f32_e32 v242, 0, v119
	v_mul_f32_e64 v149, |v119|, s51
	v_exp_f32_e32 v149, v149
	v_exp_f32_e32 v155, v155
	v_log_f32_e32 v151, v151
	v_mul_f32_e64 v157, |v175|, s51
	v_add_f32_e32 v149, 1.0, v149
	v_add_f32_e32 v153, 1.0, v153
	v_exp_f32_e32 v157, v157
	v_log_f32_e32 v244, v149
	v_log_f32_e32 v153, v153
	v_max_f32_e32 v149, 0, v172
	v_add_f32_e32 v155, 1.0, v155
	v_fmac_f32_e32 v149, 0x3f317218, v151
	v_log_f32_e32 v155, v155
	v_max_f32_e32 v151, 0, v173
	v_add_f32_e32 v157, 1.0, v157
	v_fmac_f32_e32 v151, 0x3f317218, v153
	v_log_f32_e32 v157, v157
	v_max_f32_e32 v153, 0, v174
	v_fmac_f32_e32 v153, 0x3f317218, v155
	v_max_f32_e32 v155, 0, v175
	v_fmac_f32_e32 v155, 0x3f317218, v157
	v_max_f32_e32 v177, 0, v224
	v_mul_f32_e64 v157, |v224|, s51
	v_exp_f32_e32 v157, v157
	v_sub_f32_e64 v153, -v153, v155
	v_sub_f32_e32 v151, v153, v151
	v_sub_f32_e32 v149, v151, v149
	v_add_f32_e32 v157, 1.0, v157
	v_log_f32_e32 v229, v157
	v_max_f32_e32 v231, 0, v225
	v_mul_f32_e64 v157, |v225|, s51
	v_exp_f32_e32 v157, v157
	v_mov_b32_e32 v161, v149
	ds_read_b64 v[108:109], v108
	ds_read_b64 v[110:111], v110
	v_add_f32_e32 v157, 1.0, v157
	v_log_f32_e32 v237, v157
	v_max_f32_e32 v239, 0, v226
	v_mul_f32_e64 v157, |v226|, s51
	v_exp_f32_e32 v157, v157
	v_subrev_u32_e32 v114, 64, v114
	v_add_u32_e32 v113, 0xffffee00, v113
	v_add_f32_e32 v157, 1.0, v157
	v_log_f32_e32 v241, v157
	v_max_f32_e32 v243, 0, v227
	v_mul_f32_e64 v157, |v227|, s51
	v_exp_f32_e32 v157, v157
	s_nop 0
	v_add_f32_e32 v157, 1.0, v157
	v_log_f32_e32 v245, v157
	v_mov_b32_e32 v157, v115
	s_nop 1
	v_permlane16_swap_b32_e32 v157, v159
	v_cndmask_b32_e64 v157, v157, v159, s[8:9]
	v_mov_b32_e32 v159, v149
	v_add_f32_e32 v157, v115, v157
	s_nop 0
	v_permlane16_swap_b32_e32 v159, v161
	v_cndmask_b32_e64 v159, v159, v161, s[8:9]
	v_mov_b32_e32 v161, v157
	v_mov_b32_e32 v163, v157
	v_add_f32_e32 v159, v149, v159
	s_nop 0
	v_permlane32_swap_b32_e32 v161, v163
	v_cndmask_b32_e64 v161, v161, v163, s[6:7]
	v_mov_b32_e32 v163, v159
	v_mov_b32_e32 v165, v159
	s_nop 1
	v_permlane32_swap_b32_e32 v163, v165
	v_cndmask_b32_e64 v163, v163, v165, s[6:7]
	v_add_f32_e32 v246, v159, v163
	v_sub_f32_e32 v159, v159, v149
	v_fma_f32 v159, v208, v159, v170
	v_fmac_f32_e32 v159, v209, v163
	v_add_f32_e32 v163, v170, v246
	v_sub_f32_e32 v165, v157, v115
	v_fmac_f32_e32 v163, v208, v165
	v_fmac_f32_e32 v163, v209, v161
	v_add_f32_e32 v165, v172, v159
	v_add_f32_e32 v149, v149, v165
	v_add_f32_e32 v165, v232, v163
	v_add_f32_e32 v115, v115, v165
	v_add_f32_e32 v165, v173, v159
	v_add_f32_e32 v151, v151, v165
	v_add_f32_e32 v165, v233, v163
	v_add_f32_e32 v132, v132, v165
	v_add_f32_e32 v165, v174, v159
	v_add_f32_e32 v159, v175, v159
	v_pk_fma_f32 v[174:175], v[228:229], s[62:63], v[176:177] op_sel_hi:[1,0,1]
	v_pk_fma_f32 v[176:177], v[236:237], s[62:63], v[230:231] op_sel_hi:[1,0,1]
	v_pk_fma_f32 v[228:229], v[240:241], s[62:63], v[238:239] op_sel_hi:[1,0,1]
	v_pk_fma_f32 v[230:231], v[244:245], s[62:63], v[242:243] op_sel_hi:[1,0,1]
	v_sub_f32_e32 v155, v159, v155
	v_pk_add_f32 v[228:229], v[228:229], v[230:231] neg_lo:[1,1] neg_hi:[1,1]
	v_add_f32_e32 v159, v235, v163
	v_pk_add_f32 v[176:177], v[228:229], v[176:177] neg_lo:[0,1] neg_hi:[0,1]
	v_add_f32_e32 v153, v153, v165
	v_pk_add_f32 v[174:175], v[176:177], v[174:175] neg_lo:[0,1] neg_hi:[0,1]
	v_add_f32_e32 v165, v234, v163
	v_sub_f32_e32 v143, v159, v143
	v_add_f32_e32 v172, v157, v161
	v_mov_b32_e32 v157, v174
	v_mov_b32_e32 v159, v174
	v_mov_b32_e32 v161, v175
	v_mov_b32_e32 v163, v175
	v_permlane16_swap_b32_e32 v157, v159
	s_nop 0
	v_permlane16_swap_b32_e32 v161, v163
	v_cndmask_b32_e64 v233, v161, v163, s[8:9]
	v_cndmask_b32_e64 v232, v157, v159, s[8:9]
	v_pk_add_f32 v[232:233], v[174:175], v[232:233]
	v_add_f32_e32 v141, v141, v165
	v_mov_b32_e32 v157, v232
	v_mov_b32_e32 v159, v232
	v_mov_b32_e32 v161, v233
	v_mov_b32_e32 v163, v233
	v_permlane32_swap_b32_e32 v157, v159
	s_nop 0
	v_permlane32_swap_b32_e32 v161, v163
	v_cndmask_b32_e64 v235, v161, v163, s[6:7]
	v_cndmask_b32_e64 v234, v157, v159, s[6:7]
	v_pk_add_f32 v[236:237], v[232:233], v[174:175] neg_lo:[0,1] neg_hi:[0,1]
	v_pk_add_f32 v[232:233], v[232:233], v[234:235]
	v_fma_f32 v157, v208, v237, v171
	v_add_f32_e32 v159, v171, v233
	v_fmac_f32_e32 v159, v208, v236
	v_fmac_f32_e32 v159, v209, v234
	v_add_f32_e32 v116, v116, v159
	v_add_f32_e32 v116, v174, v116
	v_fmac_f32_e32 v157, v209, v235
	v_mul_f32_e32 v116, 0x3fb8aa3b, v116
	v_exp_f32_e32 v163, v116
	v_add_f32_e32 v116, v225, v157
	v_add_f32_e32 v116, v177, v116
	v_mul_f32_e32 v116, 0x3fb8aa3b, v116
	v_exp_f32_e32 v165, v116
	v_add_f32_e32 v116, v117, v159
	v_add_f32_e32 v116, v176, v116
	v_mul_f32_e32 v116, 0x3fb8aa3b, v116
	v_exp_f32_e32 v167, v116
	v_add_f32_e32 v116, v226, v157
	v_add_f32_e32 v116, v229, v116
	v_mul_f32_e32 v116, 0x3fb8aa3b, v116
	v_exp_f32_e32 v169, v116
	v_add_f32_e32 v116, v118, v159
	v_add_f32_e32 v116, v228, v116
	v_mul_f32_e32 v116, 0x3fb8aa3b, v116
	v_exp_f32_e32 v174, v116
	v_add_f32_e32 v116, v227, v157
	v_sub_f32_e32 v116, v116, v231
	v_mul_f32_e32 v116, 0x3fb8aa3b, v116
	v_add_f32_e32 v161, v224, v157
	v_exp_f32_e32 v157, v116
	v_add_f32_e32 v116, v119, v159
	v_add_f32_e32 v161, v175, v161
	v_sub_f32_e32 v116, v116, v230
	v_mul_f32_e32 v149, 0x3fb8aa3b, v149
	v_mul_f32_e32 v115, 0x3fb8aa3b, v115
	v_mul_f32_e32 v151, 0x3fb8aa3b, v151
	v_mul_f32_e32 v132, 0x3fb8aa3b, v132
	v_mul_f32_e32 v153, 0x3fb8aa3b, v153
	v_mul_f32_e32 v141, 0x3fb8aa3b, v141
	v_mul_f32_e32 v155, 0x3fb8aa3b, v155
	v_mul_f32_e32 v143, 0x3fb8aa3b, v143
	v_mul_f32_e32 v161, 0x3fb8aa3b, v161
	v_mul_f32_e32 v116, 0x3fb8aa3b, v116
	v_exp_f32_e32 v149, v149
	v_exp_f32_e32 v115, v115
	v_exp_f32_e32 v151, v151
	v_exp_f32_e32 v132, v132
	v_exp_f32_e32 v153, v153
	v_exp_f32_e32 v141, v141
	v_exp_f32_e32 v155, v155
	v_exp_f32_e32 v143, v143
	v_exp_f32_e32 v161, v161
	v_exp_f32_e32 v159, v116
	v_mov_b32_e32 v173, v232
	v_mov_b32_e32 v247, v233
	v_pk_add_f32 v[116:117], v[172:173], v[246:247]
	v_cvt_pk_bf16_f32 v118, v149, v151
	v_pk_add_f32 v[170:171], v[170:171], v[116:117]
	v_cvt_pk_bf16_f32 v116, v115, v132
	v_cmp_gt_f32_e32 vcc, s63, v170
	v_cmp_gt_f32_e64 s[0:1], s63, v171
	v_cvt_pk_bf16_f32 v117, v141, v143
	v_cvt_pk_bf16_f32 v119, v153, v155
	v_cvt_pk_bf16_f32 v172, v163, v167
	v_cvt_pk_bf16_f32 v173, v174, v159
	v_cvt_pk_bf16_f32 v174, v161, v165
	v_cvt_pk_bf16_f32 v175, v169, v157
	s_and_b64 s[0:1], vcc, s[0:1]
	s_waitcnt lgkmcnt(4)
	v_mfma_f32_16x16x32_bf16 v[88:91], v[96:99], v[116:119], v[88:91]
	v_mfma_f32_16x16x32_bf16 v[72:75], v[96:99], v[172:175], v[72:75]
	s_mov_b64 vcc, s[0:1]
	s_cmp_eq_u64 vcc, exec
	s_cselect_b64 s[0:1], -1, 0
	v_cmp_ge_i32_e32 vcc, s22, v112
	s_or_b64 s[20:21], s[0:1], vcc
	v_mfma_f32_16x16x32_bf16 v[92:95], v[100:103], v[116:119], v[92:95]
	s_and_b64 s[20:21], exec, s[20:21]
	s_or_b64 s[16:17], s[20:21], s[16:17]
	s_andn2_b64 s[18:19], s[18:19], exec
	v_mfma_f32_16x16x32_bf16 v[76:79], v[100:103], v[172:175], v[76:79]
	s_and_b64 s[0:1], s[0:1], exec
	v_subrev_u32_e32 v112, 32, v112
	s_or_b64 s[18:19], s[18:19], s[0:1]
	s_waitcnt lgkmcnt(2)
	v_mfma_f32_16x16x32_bf16 v[84:87], v[104:107], v[116:119], v[84:87]
	v_mfma_f32_16x16x32_bf16 v[68:71], v[104:107], v[172:175], v[68:71]
	s_waitcnt lgkmcnt(0)
	v_mfma_f32_16x16x32_bf16 v[80:83], v[108:111], v[116:119], v[80:83]
	v_mfma_f32_16x16x32_bf16 v[64:67], v[108:111], v[172:175], v[64:67]
	s_andn2_b64 exec, exec, s[16:17]
	s_cbranch_execnz .LBB0_229
	s_or_b64 exec, exec, s[16:17]
	s_and_b64 s[0:1], s[18:19], exec

.LBB0_234:
	v_add_u32_e32 v132, s54, v146
	v_lshlrev_b64 v[96:97], 7, v[132:133]
	v_add_u32_e32 v132, 16, v132
	v_lshl_add_u64 v[100:101], v[172:173], 0, v[96:97]
	v_lshlrev_b64 v[104:105], 7, v[132:133]
	global_load_dwordx4 v[96:99], v[100:101], off
	v_lshl_add_u64 v[112:113], v[172:173], 0, v[104:105]
	global_load_dwordx4 v[108:111], v[112:113], off
	global_load_dwordx4 v[224:227], v[112:113], off offset:64
	v_lshl_add_u64 v[176:177], s[54:55], 1, v[174:175]
	global_load_dwordx4 v[100:103], v[100:101], off offset:64
	v_lshlrev_b32_e32 v132, 1, v122
	v_lshl_add_u64 v[176:177], v[176:177], 0, v[132:133]
	s_mov_b32 s0, 0x20000
	s_waitcnt vmcnt(3)
	v_mfma_f32_16x16x32_bf16 v[104:107], v[96:99], v[48:51], 0
	v_mfma_f32_16x16x32_bf16 v[96:99], v[96:99], v[52:55], 0
	s_waitcnt vmcnt(2)
	v_mfma_f32_16x16x32_bf16 v[116:119], v[108:111], v[48:51], 0
	s_waitcnt vmcnt(0)
	v_mfma_f32_16x16x32_bf16 v[112:115], v[100:103], v[56:59], v[104:107]
	v_mfma_f32_16x16x32_bf16 v[104:107], v[100:103], v[60:63], v[96:99]
	v_mfma_f32_16x16x32_bf16 v[108:111], v[108:111], v[52:55], 0
	s_nop 5
	v_max_f32_e32 v132, v112, v112
	v_mul_f32_e64 v141, |v112|, s51
	v_max_f32_e32 v143, v113, v113
	v_mfma_f32_16x16x32_bf16 v[116:119], v[224:227], v[56:59], v[116:119]
	v_mul_f32_e64 v149, |v113|, s51
	v_max_f32_e32 v151, v114, v114
	v_mul_f32_e64 v153, |v114|, s51
	v_max_f32_e32 v159, v104, v104
	v_mul_f32_e64 v161, |v104|, s51
	v_mul_f32_e64 v165, |v105|, s51
	v_mfma_f32_16x16x32_bf16 v[108:111], v[224:227], v[60:63], v[108:111]
	v_max_f32_e32 v224, 0, v132
	v_exp_f32_e32 v132, v141
	v_max_f32_e32 v226, 0, v143
	v_exp_f32_e32 v141, v149
	v_max_f32_e32 v228, 0, v151
	v_exp_f32_e32 v143, v153
	v_max_f32_e32 v225, 0, v159
	v_exp_f32_e32 v151, v161
	v_exp_f32_e32 v153, v165
	v_mul_f32_e64 v161, |v116|, s51
	v_mul_f32_e64 v165, |v117|, s51
	v_max_f32_e32 v232, 0, v116
	v_exp_f32_e32 v159, v161
	v_exp_f32_e32 v161, v165
	v_max_f32_e32 v229, 0, v106
	v_mul_f32_e64 v223, |v108|, s51
	v_add_f32_e32 v141, 1.0, v141
	v_max_f32_e32 v236, 0, v118
	v_exp_f32_e32 v167, v223
	v_log_f32_e32 v242, v141
	v_add_f32_e32 v141, 1.0, v161
	v_add_f32_e32 v132, 1.0, v132
	v_log_f32_e32 v250, v141
	v_mul_f32_e64 v141, |v109|, s51
	v_log_f32_e32 v240, v132
	v_add_f32_e32 v132, 1.0, v159
	v_exp_f32_e32 v141, v141
	v_log_f32_e32 v248, v132
	v_max_f32_e32 v233, 0, v108
	v_add_f32_e32 v132, 1.0, v167
	v_log_f32_e32 v249, v132
	v_max_f32_e32 v235, 0, v109
	v_add_f32_e32 v132, 1.0, v141
	v_mul_f32_e64 v141, |v110|, s51
	v_add_co_u32_e32 v98, vcc, s0, v176
	v_exp_f32_e32 v141, v141
	s_nop 0
	v_addc_co_u32_e32 v99, vcc, 0, v177, vcc
	global_load_dwordx2 v[100:101], v[176:177], off
	global_load_dwordx2 v[102:103], v[176:177], off offset:32
	global_load_dwordx2 v[96:97], v[98:99], off
	s_nop 0
	global_load_dwordx2 v[98:99], v[98:99], off offset:32
	v_mul_f32_e64 v157, |v115|, s51
	v_mul_f32_e64 v169, |v106|, s51
	v_mul_f32_e64 v179, |v107|, s51
	v_max_f32_e32 v230, 0, v115
	v_exp_f32_e32 v149, v157
	v_exp_f32_e32 v155, v169
	v_exp_f32_e32 v157, v179
	v_log_f32_e32 v251, v132
	v_max_f32_e32 v227, 0, v105
	v_mul_f32_e64 v169, |v118|, s51
	v_mul_f32_e64 v179, |v119|, s51
	v_max_f32_e32 v237, 0, v110
	v_add_f32_e32 v132, 1.0, v141
	v_mul_f32_e64 v141, |v111|, s51
	v_max_f32_e32 v234, 0, v117
	v_exp_f32_e32 v163, v169
	v_exp_f32_e32 v165, v179
	v_exp_f32_e32 v141, v141
	v_add_f32_e32 v143, 1.0, v143
	v_add_f32_e32 v149, 1.0, v149
	v_add_f32_e32 v155, 1.0, v155
	v_add_f32_e32 v157, 1.0, v157
	v_max_f32_e32 v178, v107, v107
	v_add_f32_e32 v153, 1.0, v153
	v_log_f32_e32 v244, v143
	v_log_f32_e32 v246, v149
	v_log_f32_e32 v245, v155
	v_log_f32_e32 v247, v157
	v_log_f32_e32 v253, v132
	v_max_f32_e32 v231, 0, v178
	v_add_f32_e32 v151, 1.0, v151
	v_log_f32_e32 v243, v153
	v_add_f32_e32 v143, 1.0, v163
	v_add_f32_e32 v149, 1.0, v165
	v_max_f32_e32 v239, 0, v111
	v_add_f32_e32 v132, 1.0, v141
	v_max_f32_e32 v238, 0, v119
	v_log_f32_e32 v241, v151
	v_log_f32_e32 v252, v143
	v_log_f32_e32 v178, v149
	v_log_f32_e32 v179, v132
	v_pk_fma_f32 v[228:229], v[244:245], s[62:63], v[228:229] op_sel_hi:[1,0,1]
	v_pk_fma_f32 v[230:231], v[246:247], s[62:63], v[230:231] op_sel_hi:[1,0,1]
	v_pk_fma_f32 v[226:227], v[242:243], s[62:63], v[226:227] op_sel_hi:[1,0,1]
	v_pk_add_f32 v[228:229], v[228:229], v[230:231] neg_lo:[1,1] neg_hi:[1,1]
	v_pk_fma_f32 v[224:225], v[240:241], s[62:63], v[224:225] op_sel_hi:[1,0,1]
	v_pk_fma_f32 v[236:237], v[252:253], s[62:63], v[236:237] op_sel_hi:[1,0,1]
	v_pk_fma_f32 v[178:179], v[178:179], s[62:63], v[238:239] op_sel_hi:[1,0,1]
	v_pk_add_f32 v[226:227], v[228:229], v[226:227] neg_lo:[0,1] neg_hi:[0,1]
	v_pk_fma_f32 v[234:235], v[250:251], s[62:63], v[234:235] op_sel_hi:[1,0,1]
	v_pk_add_f32 v[224:225], v[226:227], v[224:225] neg_lo:[0,1] neg_hi:[0,1]
	v_pk_add_f32 v[236:237], v[236:237], v[178:179] neg_lo:[1,1] neg_hi:[1,1]
	v_pk_fma_f32 v[232:233], v[248:249], s[62:63], v[232:233] op_sel_hi:[1,0,1]
	v_pk_add_f32 v[234:235], v[236:237], v[234:235] neg_lo:[0,1] neg_hi:[0,1]
	v_mov_b32_e32 v132, v224
	v_mov_b32_e32 v141, v224
	v_mov_b32_e32 v143, v225
	v_mov_b32_e32 v149, v225
	v_pk_add_f32 v[232:233], v[234:235], v[232:233] neg_lo:[0,1] neg_hi:[0,1]
	v_permlane16_swap_b32_e32 v132, v141
	v_permlane16_swap_b32_e32 v143, v149
	v_cndmask_b32_e64 v239, v143, v149, s[8:9]
	v_cndmask_b32_e64 v238, v132, v141, s[8:9]
	v_mov_b32_e32 v132, v232
	v_mov_b32_e32 v141, v232
	v_mov_b32_e32 v143, v233
	v_mov_b32_e32 v149, v233
	v_pk_add_f32 v[238:239], v[224:225], v[238:239]
	v_permlane16_swap_b32_e32 v132, v141
	v_permlane16_swap_b32_e32 v143, v149
	v_cndmask_b32_e64 v241, v143, v149, s[8:9]
	v_cndmask_b32_e64 v240, v132, v141, s[8:9]
	v_mov_b32_e32 v132, v238
	v_mov_b32_e32 v141, v238
	v_mov_b32_e32 v143, v239
	v_mov_b32_e32 v149, v239
	v_pk_add_f32 v[240:241], v[232:233], v[240:241]
	v_permlane32_swap_b32_e32 v132, v141
	v_permlane32_swap_b32_e32 v143, v149
	v_cndmask_b32_e64 v243, v143, v149, s[6:7]
	v_cndmask_b32_e64 v242, v132, v141, s[6:7]
	v_mov_b32_e32 v132, v240
	v_mov_b32_e32 v141, v240
	v_mov_b32_e32 v143, v241
	v_mov_b32_e32 v149, v241
	v_permlane32_swap_b32_e32 v132, v141
	s_nop 0
	v_permlane32_swap_b32_e32 v143, v149
	v_cndmask_b32_e64 v245, v143, v149, s[6:7]
	v_cndmask_b32_e64 v244, v132, v141, s[6:7]
	v_pk_add_f32 v[246:247], v[240:241], v[232:233] neg_lo:[0,1] neg_hi:[0,1]
	v_pk_add_f32 v[240:241], v[240:241], v[244:245]
	v_pk_add_f32 v[250:251], v[238:239], v[224:225] neg_lo:[0,1] neg_hi:[0,1]
	v_pk_add_f32 v[248:249], v[170:171], v[240:241]
	v_fma_f32 v132, v208, v246, v170
	v_fma_f32 v141, v208, v250, v248
	v_fmac_f32_e32 v141, v209, v242
	v_add_f32_e32 v112, v112, v141
	v_add_f32_e32 v112, v224, v112
	v_fmac_f32_e32 v132, v209, v244
	v_mul_f32_e32 v112, 0x3fb8aa3b, v112
	v_exp_f32_e32 v143, v112
	v_add_f32_e32 v112, v117, v132
	v_add_f32_e32 v112, v234, v112
	v_mul_f32_e32 v112, 0x3fb8aa3b, v112
	v_exp_f32_e32 v117, v112
	v_add_f32_e32 v112, v113, v141
	v_add_f32_e32 v112, v226, v112
	v_mul_f32_e32 v112, 0x3fb8aa3b, v112
	v_exp_f32_e32 v149, v112
	v_add_f32_e32 v112, v118, v132
	v_add_f32_e32 v112, v236, v112
	v_mul_f32_e32 v112, 0x3fb8aa3b, v112
	v_exp_f32_e32 v118, v112
	v_add_f32_e32 v112, v114, v141
	v_add_f32_e32 v112, v228, v112
	v_mul_f32_e32 v112, 0x3fb8aa3b, v112
	v_exp_f32_e32 v114, v112
	v_add_f32_e32 v112, v119, v132
	v_sub_f32_e32 v112, v112, v178
	v_mul_f32_e32 v112, 0x3fb8aa3b, v112
	v_exp_f32_e32 v119, v112
	v_add_f32_e32 v112, v115, v141
	v_sub_f32_e32 v112, v112, v230
	v_mul_f32_e32 v112, 0x3fb8aa3b, v112
	v_exp_f32_e32 v115, v112
	v_pk_add_f32 v[112:113], v[238:239], v[242:243]
	v_fmac_f32_e32 v249, v208, v251
	v_pk_add_f32 v[112:113], v[112:113], v[240:241]
	v_fmac_f32_e32 v249, v209, v243
	v_pk_add_f32 v[112:113], v[170:171], v[112:113]
	v_fmac_f32_e32 v171, v208, v247
	v_fmac_f32_e32 v171, v209, v245
	v_add_f32_e32 v108, v108, v171
	v_add_f32_e32 v104, v104, v249
	v_add_f32_e32 v108, v233, v108
	v_add_f32_e32 v104, v225, v104
	v_mul_f32_e32 v108, 0x3fb8aa3b, v108
	v_mul_f32_e32 v104, 0x3fb8aa3b, v104
	v_add_f32_e32 v116, v116, v132
	v_exp_f32_e32 v132, v108
	v_exp_f32_e32 v108, v104
	v_add_f32_e32 v104, v109, v171
	v_add_f32_e32 v104, v235, v104
	v_mul_f32_e32 v104, 0x3fb8aa3b, v104
	v_exp_f32_e32 v141, v104
	v_add_f32_e32 v104, v105, v249
	v_add_f32_e32 v104, v227, v104
	v_mul_f32_e32 v104, 0x3fb8aa3b, v104
	v_exp_f32_e32 v109, v104
	v_add_f32_e32 v104, v110, v171
	v_add_f32_e32 v104, v237, v104
	v_mul_f32_e32 v104, 0x3fb8aa3b, v104
	v_exp_f32_e32 v151, v104
	v_add_f32_e32 v104, v106, v249
	v_add_f32_e32 v104, v229, v104
	v_mul_f32_e32 v104, 0x3fb8aa3b, v104
	v_exp_f32_e32 v110, v104
	v_add_f32_e32 v104, v111, v171
	v_sub_f32_e32 v104, v104, v179
	v_mul_f32_e32 v104, 0x3fb8aa3b, v104
	v_exp_f32_e32 v111, v104
	v_add_f32_e32 v104, v107, v249
	v_add_f32_e32 v116, v232, v116
	v_sub_f32_e32 v104, v104, v231
	v_mul_f32_e32 v116, 0x3fb8aa3b, v116
	v_mul_f32_e32 v104, 0x3fb8aa3b, v104
	v_exp_f32_e32 v116, v116
	v_exp_f32_e32 v153, v104
	v_cvt_pk_bf16_f32 v104, v143, v149
	v_cvt_pk_bf16_f32 v105, v114, v115
	v_cvt_pk_bf16_f32 v106, v116, v117
	v_cvt_pk_bf16_f32 v107, v118, v119
	v_cvt_pk_bf16_f32 v108, v108, v109
	v_cvt_pk_bf16_f32 v109, v110, v153
	v_cvt_pk_bf16_f32 v110, v132, v141
	v_cvt_pk_bf16_f32 v111, v151, v111
	s_mov_b32 s0, 0x40000
	s_waitcnt vmcnt(2)
	v_mfma_f32_16x16x32_bf16 v[92:95], v[100:103], v[104:107], v[92:95]
	v_mov_b64_e32 v[170:171], v[112:113]
	v_mfma_f32_16x16x32_bf16 v[76:79], v[100:103], v[108:111], v[76:79]
	v_add_co_u32_e32 v102, vcc, s0, v176
	s_mov_b32 s0, 0x60000
	s_nop 0
	v_addc_co_u32_e32 v103, vcc, 0, v177, vcc
	v_add_co_u32_e32 v114, vcc, s0, v176
	global_load_dwordx2 v[100:101], v[102:103], off
	s_nop 0
	global_load_dwordx2 v[102:103], v[102:103], off offset:32
	v_addc_co_u32_e32 v115, vcc, 0, v177, vcc
	s_waitcnt vmcnt(2)
	v_mfma_f32_16x16x32_bf16 v[88:91], v[96:99], v[104:107], v[88:91]
	v_cmp_gt_f32_e32 vcc, s63, v112
	v_cmp_gt_f32_e64 s[0:1], s63, v113
	s_and_b64 s[0:1], vcc, s[0:1]
	v_mfma_f32_16x16x32_bf16 v[72:75], v[96:99], v[108:111], v[72:75]
	global_load_dwordx2 v[96:97], v[114:115], off
	global_load_dwordx2 v[98:99], v[114:115], off offset:32
	s_waitcnt vmcnt(2)
	v_mfma_f32_16x16x32_bf16 v[84:87], v[100:103], v[104:107], v[84:87]
	v_mfma_f32_16x16x32_bf16 v[68:71], v[100:103], v[108:111], v[68:71]
	s_waitcnt vmcnt(0)
	v_mfma_f32_16x16x32_bf16 v[80:83], v[96:99], v[104:107], v[80:83]
	v_mfma_f32_16x16x32_bf16 v[64:67], v[96:99], v[108:111], v[64:67]
	s_mov_b64 vcc, s[0:1]
	s_cmp_eq_u64 vcc, exec
	s_cselect_b64 s[0:1], -1, 0
	s_sub_i32 s54, s54, 32
	s_andn2_b64 vcc, exec, s[0:1]
	s_cbranch_vccz .LBB0_208
